# MFMA/LDS interleave: V-fragment ds_reads for the PV step of all attention loops (SEL, WIN, DIL, SB) issued before the softmax VALU section into spare registers
# speedup vs baseline: 1.0082x; 1.0082x over previous
.LBB0_713:
	v_add_u32_e32 v196, v77, v122
	v_add_u32_e32 v197, 0x2000, v196
	ds_read2_b64 v[180:183], v197 offset0:128 offset1:130
	ds_read2_b64 v[184:187], v197 offset0:132 offset1:134
	v_add_u32_e32 v197, 0x3000, v196
	ds_read2_b64 v[188:191], v197 offset0:160 offset1:162
	ds_read2_b64 v[192:195], v197 offset0:164 offset1:166
	v_sub_f32_e32 v42, v119, v41
	v_exp_f32_e32 v42, v42
	v_sub_f32_e32 v44, v118, v41
	v_exp_f32_e32 v44, v44
	v_sub_f32_e32 v45, v103, v41
	v_exp_f32_e32 v45, v45
	v_sub_f32_e32 v46, v102, v41
	v_exp_f32_e32 v46, v46
	v_sub_f32_e32 v47, v101, v41
	v_add_f32_e32 v43, 0, v42
	v_exp_f32_e32 v47, v47
	v_sub_f32_e32 v78, v100, v41
	v_add_f32_e32 v43, v44, v43
	v_exp_f32_e32 v78, v78
	v_sub_f32_e32 v99, v99, v41
	v_add_f32_e32 v43, v45, v43
	v_exp_f32_e32 v99, v99
	v_sub_f32_e32 v98, v98, v41
	v_add_f32_e32 v43, v46, v43
	v_exp_f32_e32 v98, v98
	v_sub_f32_e32 v97, v97, v41
	v_add_f32_e32 v43, v47, v43
	v_exp_f32_e32 v97, v97
	v_sub_f32_e32 v40, v40, v41
	v_add_f32_e32 v43, v78, v43
	v_exp_f32_e32 v40, v40
	v_sub_f32_e32 v39, v39, v41
	v_add_f32_e32 v43, v99, v43
	v_exp_f32_e32 v39, v39
	v_sub_f32_e32 v38, v38, v41
	v_add_f32_e32 v43, v98, v43
	v_exp_f32_e32 v100, v38
	v_add_f32_e32 v43, v97, v43
	v_add_f32_e32 v43, v40, v43
	v_add_f32_e32 v43, v39, v43
	v_sub_f32_e32 v37, v37, v41
	v_add_f32_e32 v38, v100, v43
	v_exp_f32_e32 v43, v37
	v_sub_f32_e32 v36, v36, v41
	v_exp_f32_e32 v101, v36
	v_sub_f32_e32 v35, v35, v41
	v_exp_f32_e32 v102, v35
	v_sub_f32_e32 v34, v34, v41
	v_exp_f32_e32 v41, v34
	v_add_f32_e32 v37, v43, v38
	v_add_f32_e32 v36, v101, v37
	v_add_f32_e32 v35, v102, v36
	v_add_f32_e32 v103, v41, v35
	v_fmac_f32_e32 v103, v144, v32
	v_add_u32_e32 v32, v77, v122
	v_cvt_pk_bf16_f32 v35, v45, v46
	v_add_u32_e32 v46, 0x2000, v32
	v_cvt_pk_bf16_f32 v34, v42, v44
	v_cvt_pk_bf16_f32 v37, v99, v98
	v_cvt_pk_bf16_f32 v38, v97, v40
	v_cvt_pk_bf16_f32 v39, v39, v100
	v_cvt_pk_bf16_f32 v40, v43, v101
	v_cvt_pk_bf16_f32 v36, v47, v78
	v_cvt_pk_bf16_f32 v41, v102, v41
	s_setprio 1
	s_waitcnt lgkmcnt(0)
	v_mfma_f32_32x32x16_bf16 v[16:31], v[180:183], v[34:37], v[16:31]
	v_mfma_f32_32x32x16_bf16 v[16:31], v[184:187], v[38:41], v[16:31]
	s_setprio 0
	v_add_u32_e32 v32, 0x3000, v32
	s_setprio 1
	s_waitcnt lgkmcnt(0)
	v_mfma_f32_32x32x16_bf16 v[0:15], v[188:191], v[34:37], v[0:15]
	v_mfma_f32_32x32x16_bf16 v[0:15], v[192:195], v[38:41], v[0:15]
	s_setprio 0
	v_mov_b32_e32 v144, v103
	v_mov_b32_e32 v78, v33

.LBB0_718:
	v_add_u32_e32 v196, v77, v122
	v_add_u32_e32 v197, 0x2000, v196
	ds_read2_b64 v[180:183], v197 offset0:136 offset1:138
	ds_read2_b64 v[184:187], v197 offset0:140 offset1:142
	v_add_u32_e32 v197, 0x3000, v196
	ds_read2_b64 v[188:191], v197 offset0:168 offset1:170
	ds_read2_b64 v[192:195], v197 offset0:172 offset1:174
	v_sub_f32_e32 v42, v103, v41
	v_exp_f32_e32 v42, v42
	v_sub_f32_e32 v44, v102, v41
	v_exp_f32_e32 v44, v44
	v_sub_f32_e32 v45, v101, v41
	v_exp_f32_e32 v45, v45
	v_sub_f32_e32 v46, v100, v41
	v_exp_f32_e32 v46, v46
	v_sub_f32_e32 v47, v99, v41
	v_add_f32_e32 v43, 0, v42
	v_exp_f32_e32 v47, v47
	v_sub_f32_e32 v78, v98, v41
	v_add_f32_e32 v43, v44, v43
	v_exp_f32_e32 v78, v78
	v_sub_f32_e32 v97, v97, v41
	v_add_f32_e32 v43, v45, v43
	v_exp_f32_e32 v97, v97
	v_sub_f32_e32 v96, v96, v41
	v_add_f32_e32 v43, v46, v43
	v_exp_f32_e32 v96, v96
	v_sub_f32_e32 v79, v79, v41
	v_add_f32_e32 v43, v47, v43
	v_exp_f32_e32 v79, v79
	v_sub_f32_e32 v40, v40, v41
	v_add_f32_e32 v43, v78, v43
	v_exp_f32_e32 v40, v40
	v_sub_f32_e32 v39, v39, v41
	v_add_f32_e32 v43, v97, v43
	v_exp_f32_e32 v39, v39
	v_sub_f32_e32 v38, v38, v41
	v_add_f32_e32 v43, v96, v43
	v_exp_f32_e32 v98, v38
	v_add_f32_e32 v43, v79, v43
	v_add_f32_e32 v43, v40, v43
	v_add_f32_e32 v43, v39, v43
	v_sub_f32_e32 v37, v37, v41
	v_add_f32_e32 v38, v98, v43
	v_exp_f32_e32 v43, v37
	v_sub_f32_e32 v36, v36, v41
	v_exp_f32_e32 v99, v36
	v_sub_f32_e32 v35, v35, v41
	v_exp_f32_e32 v100, v35
	v_sub_f32_e32 v34, v34, v41
	v_exp_f32_e32 v41, v34
	v_add_f32_e32 v37, v43, v38
	v_add_f32_e32 v36, v99, v37
	v_add_f32_e32 v35, v100, v36
	v_add_f32_e32 v101, v41, v35
	v_fmac_f32_e32 v101, v144, v32
	v_add_u32_e32 v32, v77, v122
	v_cvt_pk_bf16_f32 v35, v45, v46
	v_add_u32_e32 v46, 0x2000, v32
	v_cvt_pk_bf16_f32 v34, v42, v44
	v_cvt_pk_bf16_f32 v37, v97, v96
	v_cvt_pk_bf16_f32 v38, v79, v40
	v_cvt_pk_bf16_f32 v39, v39, v98
	v_cvt_pk_bf16_f32 v40, v43, v99
	v_cvt_pk_bf16_f32 v36, v47, v78
	v_cvt_pk_bf16_f32 v41, v100, v41
	s_setprio 1
	s_waitcnt lgkmcnt(0)
	v_mfma_f32_32x32x16_bf16 v[16:31], v[180:183], v[34:37], v[16:31]
	v_mfma_f32_32x32x16_bf16 v[16:31], v[184:187], v[38:41], v[16:31]
	s_setprio 0
	v_add_u32_e32 v32, 0x3000, v32
	s_setprio 1
	s_waitcnt lgkmcnt(0)
	v_mfma_f32_32x32x16_bf16 v[0:15], v[188:191], v[34:37], v[0:15]
	v_mfma_f32_32x32x16_bf16 v[0:15], v[192:195], v[38:41], v[0:15]
	s_setprio 0
	v_mov_b32_e32 v144, v101
	v_mov_b32_e32 v78, v33

.LBB0_731:
	v_add_u32_e32 v196, v150, v122
	v_add_u32_e32 v197, 0x2000, v196
	ds_read2_b64 v[180:183], v197 offset0:128 offset1:130
	ds_read2_b64 v[184:187], v197 offset0:132 offset1:134
	v_add_u32_e32 v197, 0x3000, v196
	ds_read2_b64 v[188:191], v197 offset0:160 offset1:162
	ds_read2_b64 v[192:195], v197 offset0:164 offset1:166
	v_sub_f32_e32 v73, v162, v69
	v_exp_f32_e32 v73, v73
	v_sub_f32_e32 v75, v161, v69
	v_exp_f32_e32 v75, v75
	v_sub_f32_e32 v76, v160, v69
	v_exp_f32_e32 v76, v76
	v_sub_f32_e32 v77, v159, v69
	v_exp_f32_e32 v77, v77
	v_sub_f32_e32 v78, v158, v69
	v_add_f32_e32 v74, 0, v73
	v_exp_f32_e32 v78, v78
	v_sub_f32_e32 v79, v157, v69
	v_add_f32_e32 v74, v75, v74
	v_exp_f32_e32 v79, v79
	v_sub_f32_e32 v151, v156, v69
	v_add_f32_e32 v74, v76, v74
	v_exp_f32_e32 v151, v151
	v_sub_f32_e32 v155, v155, v69
	v_add_f32_e32 v74, v77, v74
	v_exp_f32_e32 v155, v155
	v_sub_f32_e32 v154, v154, v69
	v_add_f32_e32 v74, v78, v74
	v_exp_f32_e32 v154, v154
	v_sub_f32_e32 v72, v72, v69
	v_add_f32_e32 v74, v79, v74
	v_exp_f32_e32 v72, v72
	v_sub_f32_e32 v71, v71, v69
	v_add_f32_e32 v74, v151, v74
	v_exp_f32_e32 v71, v71
	v_sub_f32_e32 v70, v70, v69
	v_add_f32_e32 v74, v155, v74
	v_exp_f32_e32 v70, v70
	v_sub_f32_e32 v68, v68, v69
	v_add_f32_e32 v74, v154, v74
	v_exp_f32_e32 v156, v68
	v_add_f32_e32 v74, v72, v74
	v_add_f32_e32 v74, v71, v74
	v_add_f32_e32 v74, v70, v74
	v_sub_f32_e32 v67, v67, v69
	v_add_f32_e32 v68, v156, v74
	v_exp_f32_e32 v74, v67
	v_sub_f32_e32 v66, v66, v69
	v_exp_f32_e32 v157, v66
	v_sub_f32_e32 v65, v65, v69
	v_exp_f32_e32 v158, v65
	v_add_f32_e32 v67, v74, v68
	v_add_f32_e32 v66, v157, v67
	v_cvt_pk_bf16_f32 v65, v76, v77
	v_add_f32_e32 v159, v158, v66
	v_fmac_f32_e32 v159, v149, v64
	v_add_u32_e32 v149, v150, v122
	v_add_u32_e32 v76, 0x2000, v149
	v_cvt_pk_bf16_f32 v64, v73, v75
	v_cvt_pk_bf16_f32 v66, v78, v79
	v_cvt_pk_bf16_f32 v68, v154, v72
	v_cvt_pk_bf16_f32 v69, v71, v70
	v_cvt_pk_bf16_f32 v70, v156, v74
	v_cvt_pk_bf16_f32 v67, v151, v155
	v_cvt_pk_bf16_f32 v71, v157, v158
	s_setprio 1
	s_waitcnt lgkmcnt(0)
	v_mfma_f32_32x32x16_bf16 v[48:63], v[180:183], v[64:67], v[48:63]
	v_mfma_f32_32x32x16_bf16 v[48:63], v[184:187], v[68:71], v[48:63]
	s_setprio 0
	s_setprio 1
	s_waitcnt lgkmcnt(0)
	v_mfma_f32_32x32x16_bf16 v[32:47], v[188:191], v[64:67], v[32:47]
	v_mfma_f32_32x32x16_bf16 v[32:47], v[192:195], v[68:71], v[32:47]
	s_setprio 0
	v_mov_b32_e32 v149, v159
	s_branch .LBB0_733

.LBB0_736:
	v_add_u32_e32 v196, v150, v122
	v_add_u32_e32 v197, 0x2000, v196
	ds_read2_b64 v[180:183], v197 offset0:136 offset1:138
	ds_read2_b64 v[184:187], v197 offset0:140 offset1:142
	v_add_u32_e32 v197, 0x3000, v196
	ds_read2_b64 v[188:191], v197 offset0:168 offset1:170
	ds_read2_b64 v[192:195], v197 offset0:172 offset1:174
	v_sub_f32_e32 v73, v161, v69
	v_exp_f32_e32 v73, v73
	v_sub_f32_e32 v75, v160, v69
	v_exp_f32_e32 v75, v75
	v_sub_f32_e32 v76, v159, v69
	v_exp_f32_e32 v76, v76
	v_sub_f32_e32 v77, v158, v69
	v_exp_f32_e32 v77, v77
	v_sub_f32_e32 v78, v157, v69
	v_add_f32_e32 v74, 0, v73
	v_exp_f32_e32 v78, v78
	v_sub_f32_e32 v79, v156, v69
	v_add_f32_e32 v74, v75, v74
	v_exp_f32_e32 v79, v79
	v_sub_f32_e32 v153, v155, v69
	v_add_f32_e32 v74, v76, v74
	v_exp_f32_e32 v153, v153
	v_sub_f32_e32 v154, v154, v69
	v_add_f32_e32 v74, v77, v74
	v_exp_f32_e32 v154, v154
	v_sub_f32_e32 v152, v152, v69
	v_add_f32_e32 v74, v78, v74
	v_exp_f32_e32 v152, v152
	v_sub_f32_e32 v72, v72, v69
	v_add_f32_e32 v74, v79, v74
	v_exp_f32_e32 v72, v72
	v_sub_f32_e32 v71, v71, v69
	v_add_f32_e32 v74, v153, v74
	v_exp_f32_e32 v71, v71
	v_sub_f32_e32 v70, v70, v69
	v_add_f32_e32 v74, v154, v74
	v_exp_f32_e32 v70, v70
	v_sub_f32_e32 v68, v68, v69
	v_add_f32_e32 v74, v152, v74
	v_exp_f32_e32 v155, v68
	v_add_f32_e32 v74, v72, v74
	v_add_f32_e32 v74, v71, v74
	v_add_f32_e32 v74, v70, v74
	v_sub_f32_e32 v67, v67, v69
	v_add_f32_e32 v68, v155, v74
	v_exp_f32_e32 v74, v67
	v_sub_f32_e32 v66, v66, v69
	v_exp_f32_e32 v156, v66
	v_sub_f32_e32 v65, v65, v69
	v_exp_f32_e32 v157, v65
	v_add_f32_e32 v67, v74, v68
	v_add_f32_e32 v66, v156, v67
	v_cvt_pk_bf16_f32 v65, v76, v77
	v_add_f32_e32 v158, v157, v66
	v_fmac_f32_e32 v158, v149, v64
	v_add_u32_e32 v149, v150, v122
	v_add_u32_e32 v76, 0x2000, v149
	v_cvt_pk_bf16_f32 v64, v73, v75
	v_cvt_pk_bf16_f32 v66, v78, v79
	v_cvt_pk_bf16_f32 v68, v152, v72
	v_cvt_pk_bf16_f32 v69, v71, v70
	v_cvt_pk_bf16_f32 v70, v155, v74
	v_cvt_pk_bf16_f32 v67, v153, v154
	v_cvt_pk_bf16_f32 v71, v156, v157
	s_setprio 1
	s_waitcnt lgkmcnt(0)
	v_mfma_f32_32x32x16_bf16 v[48:63], v[180:183], v[64:67], v[48:63]
	v_mfma_f32_32x32x16_bf16 v[48:63], v[184:187], v[68:71], v[48:63]
	s_setprio 0
	s_setprio 1
	s_waitcnt lgkmcnt(0)
	v_mfma_f32_32x32x16_bf16 v[32:47], v[188:191], v[64:67], v[32:47]
	v_mfma_f32_32x32x16_bf16 v[32:47], v[192:195], v[68:71], v[32:47]
	s_setprio 0
	v_mov_b32_e32 v149, v158
	s_branch .LBB0_725

.LBB0_765:
	v_add_u32_e32 v196, v99, v111
	v_add_u32_e32 v197, 0x2000, v196
	ds_read2_b64 v[180:183], v197 offset0:128 offset1:130
	ds_read2_b64 v[184:187], v197 offset0:132 offset1:134
	v_add_u32_e32 v197, 0x3000, v196
	ds_read2_b64 v[188:191], v197 offset0:160 offset1:162
	ds_read2_b64 v[192:195], v197 offset0:164 offset1:166
	v_sub_f32_e32 v32, v32, v49
	v_exp_f32_e32 v32, v32
	v_sub_f32_e32 v33, v33, v49
	v_exp_f32_e32 v33, v33
	v_sub_f32_e32 v34, v34, v49
	v_exp_f32_e32 v34, v34
	v_sub_f32_e32 v35, v35, v49
	v_exp_f32_e32 v35, v35
	v_sub_f32_e32 v36, v36, v49
	v_add_f32_e32 v50, 0, v32
	v_exp_f32_e32 v36, v36
	v_sub_f32_e32 v37, v37, v49
	v_add_f32_e32 v50, v33, v50
	v_exp_f32_e32 v37, v37
	v_sub_f32_e32 v38, v38, v49
	v_add_f32_e32 v50, v34, v50
	v_exp_f32_e32 v38, v38
	v_sub_f32_e32 v39, v39, v49
	v_add_f32_e32 v50, v35, v50
	v_exp_f32_e32 v39, v39
	v_sub_f32_e32 v40, v40, v49
	v_add_f32_e32 v50, v36, v50
	v_exp_f32_e32 v40, v40
	v_sub_f32_e32 v41, v41, v49
	v_add_f32_e32 v50, v37, v50
	v_exp_f32_e32 v41, v41
	v_sub_f32_e32 v42, v42, v49
	v_add_f32_e32 v50, v38, v50
	v_exp_f32_e32 v42, v42
	v_sub_f32_e32 v43, v43, v49
	v_add_f32_e32 v50, v39, v50
	v_exp_f32_e32 v43, v43
	v_sub_f32_e32 v44, v44, v49
	v_add_f32_e32 v50, v40, v50
	v_exp_f32_e32 v44, v44
	v_sub_f32_e32 v45, v45, v49
	v_add_f32_e32 v50, v41, v50
	v_exp_f32_e32 v45, v45
	v_sub_f32_e32 v46, v46, v49
	v_add_f32_e32 v50, v42, v50
	v_exp_f32_e32 v46, v46
	v_sub_f32_e32 v47, v47, v49
	v_add_f32_e32 v50, v43, v50
	v_exp_f32_e32 v47, v47
	v_add_f32_e32 v50, v44, v50
	v_add_f32_e32 v50, v45, v50
	v_add_f32_e32 v50, v46, v50
	v_add_f32_e32 v49, v47, v50
	v_fmac_f32_e32 v49, v103, v48
	v_add_u32_e32 v48, v99, v111
	v_cvt_pk_bf16_f32 v32, v32, v33
	v_cvt_pk_bf16_f32 v33, v34, v35
	v_cvt_pk_bf16_f32 v35, v38, v39
	v_cvt_pk_bf16_f32 v38, v44, v45
	v_add_u32_e32 v44, 0x2000, v48
	v_cvt_pk_bf16_f32 v34, v36, v37
	v_cvt_pk_bf16_f32 v36, v40, v41
	v_cvt_pk_bf16_f32 v37, v42, v43
	v_cvt_pk_bf16_f32 v39, v46, v47
	s_setprio 1
	s_waitcnt lgkmcnt(0)
	v_mfma_f32_32x32x16_bf16 v[16:31], v[180:183], v[32:35], v[16:31]
	v_mfma_f32_32x32x16_bf16 v[16:31], v[184:187], v[36:39], v[16:31]
	s_setprio 0
	s_setprio 1
	s_waitcnt lgkmcnt(0)
	v_mfma_f32_32x32x16_bf16 v[0:15], v[188:191], v[32:35], v[0:15]
	v_mfma_f32_32x32x16_bf16 v[0:15], v[192:195], v[36:39], v[0:15]
	s_setprio 0
	v_mov_b32_e32 v103, v49
	s_cmp_gt_i32 s92, s86
	s_cbranch_scc1 .LBB0_746
	s_branch .LBB0_767

.LBB0_781:
	v_add_u32_e32 v196, v99, v111
	v_add_u32_e32 v197, 0x2000, v196
	ds_read2_b64 v[180:183], v197 offset0:136 offset1:138
	ds_read2_b64 v[184:187], v197 offset0:140 offset1:142
	v_add_u32_e32 v197, 0x3000, v196
	ds_read2_b64 v[188:191], v197 offset0:168 offset1:170
	ds_read2_b64 v[192:195], v197 offset0:172 offset1:174
	v_sub_f32_e32 v32, v32, v49
	v_exp_f32_e32 v32, v32
	v_sub_f32_e32 v33, v33, v49
	v_exp_f32_e32 v33, v33
	v_sub_f32_e32 v34, v34, v49
	v_exp_f32_e32 v34, v34
	v_sub_f32_e32 v35, v35, v49
	v_exp_f32_e32 v35, v35
	v_sub_f32_e32 v36, v36, v49
	v_add_f32_e32 v50, 0, v32
	v_exp_f32_e32 v36, v36
	v_sub_f32_e32 v37, v37, v49
	v_add_f32_e32 v50, v33, v50
	v_exp_f32_e32 v37, v37
	v_sub_f32_e32 v38, v38, v49
	v_add_f32_e32 v50, v34, v50
	v_exp_f32_e32 v38, v38
	v_sub_f32_e32 v39, v39, v49
	v_add_f32_e32 v50, v35, v50
	v_exp_f32_e32 v39, v39
	v_sub_f32_e32 v40, v40, v49
	v_add_f32_e32 v50, v36, v50
	v_exp_f32_e32 v40, v40
	v_sub_f32_e32 v41, v41, v49
	v_add_f32_e32 v50, v37, v50
	v_exp_f32_e32 v41, v41
	v_sub_f32_e32 v42, v42, v49
	v_add_f32_e32 v50, v38, v50
	v_exp_f32_e32 v42, v42
	v_sub_f32_e32 v43, v43, v49
	v_add_f32_e32 v50, v39, v50
	v_exp_f32_e32 v43, v43
	v_sub_f32_e32 v44, v44, v49
	v_add_f32_e32 v50, v40, v50
	v_exp_f32_e32 v44, v44
	v_sub_f32_e32 v45, v45, v49
	v_add_f32_e32 v50, v41, v50
	v_exp_f32_e32 v45, v45
	v_sub_f32_e32 v46, v46, v49
	v_add_f32_e32 v50, v42, v50
	v_exp_f32_e32 v46, v46
	v_sub_f32_e32 v47, v47, v49
	v_add_f32_e32 v50, v43, v50
	v_exp_f32_e32 v47, v47
	v_add_f32_e32 v50, v44, v50
	v_add_f32_e32 v50, v45, v50
	v_add_f32_e32 v50, v46, v50
	v_add_f32_e32 v49, v47, v50
	v_fmac_f32_e32 v49, v103, v48
	v_add_u32_e32 v48, v99, v111
	v_cvt_pk_bf16_f32 v32, v32, v33
	v_cvt_pk_bf16_f32 v33, v34, v35
	v_cvt_pk_bf16_f32 v35, v38, v39
	v_cvt_pk_bf16_f32 v38, v44, v45
	v_add_u32_e32 v44, 0x2000, v48
	v_cvt_pk_bf16_f32 v34, v36, v37
	v_cvt_pk_bf16_f32 v36, v40, v41
	v_cvt_pk_bf16_f32 v37, v42, v43
	v_cvt_pk_bf16_f32 v39, v46, v47
	s_setprio 1
	s_waitcnt lgkmcnt(0)
	v_mfma_f32_32x32x16_bf16 v[16:31], v[180:183], v[32:35], v[16:31]
	v_mfma_f32_32x32x16_bf16 v[16:31], v[184:187], v[36:39], v[16:31]
	s_setprio 0
	s_setprio 1
	s_waitcnt lgkmcnt(0)
	v_mfma_f32_32x32x16_bf16 v[0:15], v[188:191], v[32:35], v[0:15]
	v_mfma_f32_32x32x16_bf16 v[0:15], v[192:195], v[36:39], v[0:15]
	s_setprio 0
	v_mov_b32_e32 v103, v49
	s_branch .LBB0_747

.LBB0_791:
	s_add_i32 s16, s6, 0x60
	s_cmp_le_i32 s16, s18
	s_cselect_b64 s[16:17], -1, 0
	v_add_u32_e32 v32, s33, v97
	v_add_u32_e32 v33, s33, v88
	s_and_b64 s[16:17], s[16:17], s[14:15]
	s_andn2_b64 vcc, exec, s[16:17]
	v_add_u32_e32 v82, v32, v112
	v_add_u32_e32 v81, s6, v96
	v_add_u32_e32 v80, v33, v111
	s_cbranch_vccnz .LBB0_793
	ds_read_b128 v[32:35], v82 offset:4608
	ds_read_b128 v[84:87], v82 offset:4640
	ds_read_b128 v[106:109], v82 offset:4672
	ds_read_b128 v[120:123], v82 offset:4704
	s_setprio 1
	s_waitcnt lgkmcnt(0)
	v_mfma_f32_32x32x16_bf16 v[32:47], v[32:35], v[64:67], 0
	v_mfma_f32_32x32x16_bf16 v[32:47], v[84:87], v[68:71], v[32:47]
	v_mfma_f32_32x32x16_bf16 v[32:47], v[106:109], v[72:75], v[32:47]
	v_mfma_f32_32x32x16_bf16 v[32:47], v[120:123], v[76:79], v[32:47]
	s_setprio 0
	s_nop 10
	v_add_u32_e32 v197, 0x2000, v80
	ds_read2_b64 v[180:183], v197 offset0:136 offset1:138
	ds_read2_b64 v[184:187], v197 offset0:140 offset1:142
	v_add_u32_e32 v197, 0x3000, v80
	ds_read2_b64 v[188:191], v197 offset0:168 offset1:170
	ds_read2_b64 v[192:195], v197 offset0:172 offset1:174
	v_mul_f32_e32 v60, 0x3e000000, v32
	v_mul_f32_e64 v61, |v60|, s37
	v_exp_f32_e32 v61, v61
	v_mul_f32_e32 v84, 0x3e000000, v33
	v_add_u32_e32 v62, 0x60, v81
	v_max_f32_e32 v60, 0, v60
	v_add_f32_e32 v61, 1.0, v61
	s_nop 1
	v_log_f32_e32 v61, v61
	s_nop 0
	v_mul_f32_e32 v85, 0x3f317217, v61
	v_fma_f32 v85, v61, s83, -v85
	v_fmac_f32_e32 v85, 0x3377d1cf, v61
	v_fmac_f32_e32 v85, 0x3f317217, v61
	s_nop 1
	v_mov_b32_e32 v61, v85
	v_mul_f32_e64 v83, |v84|, s37
	v_exp_f32_e32 v83, v83
	v_cmp_lt_i32_e32 vcc, v62, v102
	v_add_f32_e32 v61, v60, v61
	v_fma_f32 v32, v32, s81, -v61
	v_add_f32_e32 v62, 1.0, v83
	v_cndmask_b32_e64 v60, 0, -v61, vcc
	s_nop 0
	v_log_f32_e32 v62, v62
	s_nop 0
	v_cndmask_b32_e32 v83, v212, v32, vcc
	v_max_f32_e32 v32, 0, v84
	v_mul_f32_e32 v61, 0x3f317217, v62
	v_fma_f32 v61, v62, s83, -v61
	v_fmac_f32_e32 v61, 0x3377d1cf, v62
	v_fmac_f32_e32 v61, 0x3f317217, v62
	s_nop 1
	v_mul_f32_e32 v62, 0x3e000000, v34
	v_add_f32_e32 v61, v32, v61
	v_mul_f32_e64 v32, |v62|, s37
	v_exp_f32_e32 v84, v32
	v_add_u32_e32 v32, 0x61, v81
	v_cmp_lt_i32_e32 vcc, v32, v102
	v_fma_f32 v33, v33, s81, -v61
	v_add_f32_e32 v84, 1.0, v84
	v_cndmask_b32_e64 v32, 0, -v61, vcc
	s_nop 0
	v_log_f32_e32 v85, v84
	s_nop 0
	v_cndmask_b32_e32 v84, v212, v33, vcc
	v_max_f32_e32 v33, 0, v62
	v_mul_f32_e32 v61, 0x3f317217, v85
	v_fma_f32 v61, v85, s83, -v61
	v_fmac_f32_e32 v61, 0x3377d1cf, v85
	v_fmac_f32_e32 v61, 0x3f317217, v85
	s_nop 1
	v_add_f32_e32 v33, v33, v61
	v_mul_f32_e32 v61, 0x3e000000, v35
	v_mul_f32_e64 v62, |v61|, s37
	v_exp_f32_e32 v85, v62
	v_add_u32_e32 v62, 0x62, v81
	v_cmp_lt_i32_e32 vcc, v62, v102
	v_add_f32_e32 v85, 1.0, v85
	v_cndmask_b32_e64 v62, 0, -v33, vcc
	v_fma_f32 v33, v34, s81, -v33
	v_log_f32_e32 v85, v85
	s_nop 0
	v_cndmask_b32_e32 v86, v212, v33, vcc
	v_max_f32_e32 v33, 0, v61
	v_mul_f32_e32 v34, 0x3f317217, v85
	v_fma_f32 v34, v85, s83, -v34
	v_fmac_f32_e32 v34, 0x3377d1cf, v85
	v_fmac_f32_e32 v34, 0x3f317217, v85
	s_nop 1
	v_mul_f32_e32 v61, 0x3e000000, v36
	v_add_f32_e32 v33, v33, v34
	v_mul_f32_e64 v34, |v61|, s37
	v_exp_f32_e32 v85, v34
	v_add_u32_e32 v34, 0x63, v81
	v_cmp_lt_i32_e32 vcc, v34, v102
	v_add_f32_e32 v85, 1.0, v85
	v_cndmask_b32_e64 v34, 0, -v33, vcc
	v_fma_f32 v33, v35, s81, -v33
	v_log_f32_e32 v85, v85
	s_nop 0
	v_cndmask_b32_e32 v87, v212, v33, vcc
	v_max_f32_e32 v33, 0, v61
	v_mul_f32_e32 v35, 0x3f317217, v85
	v_fma_f32 v35, v85, s83, -v35
	v_fmac_f32_e32 v35, 0x3377d1cf, v85
	v_fmac_f32_e32 v35, 0x3f317217, v85
	s_nop 1
	v_add_f32_e32 v33, v33, v35
	v_mul_f32_e32 v35, 0x3e000000, v37
	v_mul_f32_e64 v61, |v35|, s37
	v_exp_f32_e32 v61, v61
	v_add_u32_e32 v85, 0x68, v81
	v_cmp_lt_i32_e32 vcc, v85, v102
	v_add_f32_e32 v61, 1.0, v61
	v_cndmask_b32_e64 v85, 0, -v33, vcc
	v_fma_f32 v33, v36, s81, -v33
	v_log_f32_e32 v61, v61
	s_nop 0
	v_cndmask_b32_e32 v99, v212, v33, vcc
	v_max_f32_e32 v33, 0, v35
	v_mul_f32_e32 v35, 0x3f317217, v61
	v_fma_f32 v35, v61, s83, -v35
	v_fmac_f32_e32 v35, 0x3377d1cf, v61
	v_fmac_f32_e32 v35, 0x3f317217, v61
	s_nop 1
	v_add_f32_e32 v33, v33, v35
	v_mul_f32_e32 v35, 0x3e000000, v38
	v_mul_f32_e64 v36, |v35|, s37
	v_exp_f32_e32 v36, v36
	v_add_u32_e32 v61, 0x69, v81
	v_cmp_lt_i32_e32 vcc, v61, v102
	v_add_f32_e32 v36, 1.0, v36
	v_cndmask_b32_e64 v103, 0, -v33, vcc
	v_fma_f32 v33, v37, s81, -v33
	v_log_f32_e32 v36, v36
	s_nop 0
	v_cndmask_b32_e32 v105, v212, v33, vcc
	v_max_f32_e32 v33, 0, v35
	v_add_u32_e32 v37, 0x6a, v81
	v_mul_f32_e32 v35, 0x3f317217, v36
	v_fma_f32 v35, v36, s83, -v35
	v_fmac_f32_e32 v35, 0x3377d1cf, v36
	v_fmac_f32_e32 v35, 0x3f317217, v36
	s_nop 1
	v_add_f32_e32 v33, v33, v35
	v_mul_f32_e32 v35, 0x3e000000, v39
	v_mul_f32_e64 v36, |v35|, s37
	v_exp_f32_e32 v36, v36
	v_cmp_lt_i32_e32 vcc, v37, v102
	v_add_f32_e32 v36, 1.0, v36
	v_cndmask_b32_e64 v106, 0, -v33, vcc
	v_fma_f32 v33, v38, s81, -v33
	v_log_f32_e32 v36, v36
	s_nop 0
	v_cndmask_b32_e32 v107, v212, v33, vcc
	v_max_f32_e32 v33, 0, v35
	v_add_u32_e32 v37, 0x6b, v81
	v_mul_f32_e32 v35, 0x3f317217, v36
	v_fma_f32 v35, v36, s83, -v35
	v_fmac_f32_e32 v35, 0x3377d1cf, v36
	v_fmac_f32_e32 v35, 0x3f317217, v36
	s_nop 1
	v_add_f32_e32 v33, v33, v35
	v_mul_f32_e32 v35, 0x3e000000, v40
	v_mul_f32_e64 v36, |v35|, s37
	v_exp_f32_e32 v36, v36
	v_cmp_lt_i32_e32 vcc, v37, v102
	v_add_f32_e32 v36, 1.0, v36
	v_cndmask_b32_e64 v108, 0, -v33, vcc
	v_fma_f32 v33, v39, s81, -v33
	v_log_f32_e32 v36, v36
	s_nop 0
	v_cndmask_b32_e32 v109, v212, v33, vcc
	v_max_f32_e32 v33, 0, v35
	v_add_u32_e32 v37, 0x70, v81
	v_mul_f32_e32 v35, 0x3f317217, v36
	v_fma_f32 v35, v36, s83, -v35
	v_fmac_f32_e32 v35, 0x3377d1cf, v36
	v_fmac_f32_e32 v35, 0x3f317217, v36
	v_add_u32_e32 v39, 0x71, v81
	s_nop 0
	v_add_f32_e32 v33, v33, v35
	v_mul_f32_e32 v35, 0x3e000000, v41
	v_mul_f32_e64 v36, |v35|, s37
	v_exp_f32_e32 v36, v36
	v_cmp_lt_i32_e32 vcc, v37, v102
	v_add_f32_e32 v36, 1.0, v36
	v_cndmask_b32_e64 v37, 0, -v33, vcc
	v_fma_f32 v33, v40, s81, -v33
	v_log_f32_e32 v36, v36
	s_nop 0
	v_cndmask_b32_e32 v38, v212, v33, vcc
	v_max_f32_e32 v33, 0, v35
	v_mul_f32_e32 v35, 0x3f317217, v36
	v_fma_f32 v35, v36, s83, -v35
	v_fmac_f32_e32 v35, 0x3377d1cf, v36
	v_fmac_f32_e32 v35, 0x3f317217, v36
	s_nop 1
	v_add_f32_e32 v33, v33, v35
	v_mul_f32_e32 v35, 0x3e000000, v42
	v_mul_f32_e64 v36, |v35|, s37
	v_exp_f32_e32 v36, v36
	v_cmp_lt_i32_e32 vcc, v39, v102
	v_add_f32_e32 v36, 1.0, v36
	v_cndmask_b32_e64 v39, 0, -v33, vcc
	v_fma_f32 v33, v41, s81, -v33
	v_log_f32_e32 v36, v36
	s_nop 0
	v_cndmask_b32_e32 v40, v212, v33, vcc
	v_max_f32_e32 v33, 0, v35
	v_add_u32_e32 v41, 0x72, v81
	v_mul_f32_e32 v35, 0x3f317217, v36
	v_fma_f32 v35, v36, s83, -v35
	v_fmac_f32_e32 v35, 0x3377d1cf, v36
	v_fmac_f32_e32 v35, 0x3f317217, v36
	v_add_f32_e32 v37, v37, v39
	s_nop 0
	v_add_f32_e32 v33, v33, v35
	v_mul_f32_e32 v35, 0x3e000000, v43
	v_mul_f32_e64 v36, |v35|, s37
	v_exp_f32_e32 v36, v36
	v_cmp_lt_i32_e32 vcc, v41, v102
	v_add_f32_e32 v36, 1.0, v36
	v_cndmask_b32_e64 v41, 0, -v33, vcc
	v_fma_f32 v33, v42, s81, -v33
	v_log_f32_e32 v36, v36
	s_nop 0
	v_cndmask_b32_e32 v42, v212, v33, vcc
	v_max_f32_e32 v33, 0, v35
	v_add_u32_e32 v61, 0x73, v81
	v_mul_f32_e32 v35, 0x3f317217, v36
	v_fma_f32 v35, v36, s83, -v35
	v_fmac_f32_e32 v35, 0x3377d1cf, v36
	v_fmac_f32_e32 v35, 0x3f317217, v36
	s_nop 1
	v_add_f32_e32 v33, v33, v35
	v_mul_f32_e32 v35, 0x3e000000, v44
	v_mul_f32_e64 v36, |v35|, s37
	v_exp_f32_e32 v36, v36
	v_cmp_lt_i32_e32 vcc, v61, v102
	v_add_f32_e32 v36, 1.0, v36
	v_cndmask_b32_e64 v120, 0, -v33, vcc
	v_fma_f32 v33, v43, s81, -v33
	v_log_f32_e32 v36, v36
	s_nop 0
	v_cndmask_b32_e32 v43, v212, v33, vcc
	v_max_f32_e32 v33, 0, v35
	v_add_u32_e32 v61, 0x78, v81
	v_mul_f32_e32 v35, 0x3f317217, v36
	v_fma_f32 v35, v36, s83, -v35
	v_fmac_f32_e32 v35, 0x3377d1cf, v36
	v_fmac_f32_e32 v35, 0x3f317217, v36
	s_nop 1
	v_add_f32_e32 v33, v33, v35
	v_mul_f32_e32 v35, 0x3e000000, v45
	v_mul_f32_e64 v36, |v35|, s37
	v_exp_f32_e32 v36, v36
	v_cmp_lt_i32_e32 vcc, v61, v102
	v_add_f32_e32 v36, 1.0, v36
	v_cndmask_b32_e64 v121, 0, -v33, vcc
	v_fma_f32 v33, v44, s81, -v33
	v_log_f32_e32 v36, v36
	s_nop 0
	v_cndmask_b32_e32 v44, v212, v33, vcc
	v_max_f32_e32 v33, 0, v35
	v_add_u32_e32 v61, 0x79, v81
	v_mul_f32_e32 v35, 0x3f317217, v36
	v_fma_f32 v35, v36, s83, -v35
	v_fmac_f32_e32 v35, 0x3377d1cf, v36
	v_fmac_f32_e32 v35, 0x3f317217, v36
	s_nop 1
	v_add_f32_e32 v33, v33, v35
	v_mul_f32_e32 v35, 0x3e000000, v46
	v_mul_f32_e64 v36, |v35|, s37
	v_exp_f32_e32 v36, v36
	v_cmp_lt_i32_e32 vcc, v61, v102
	v_add_f32_e32 v36, 1.0, v36
	v_cndmask_b32_e64 v122, 0, -v33, vcc
	v_fma_f32 v33, v45, s81, -v33
	v_log_f32_e32 v36, v36
	s_nop 0
	v_cndmask_b32_e32 v45, v212, v33, vcc
	v_max_f32_e32 v33, 0, v35
	v_add_u32_e32 v61, 0x7a, v81
	v_mul_f32_e32 v35, 0x3f317217, v36
	v_fma_f32 v35, v36, s83, -v35
	v_fmac_f32_e32 v35, 0x3377d1cf, v36
	v_fmac_f32_e32 v35, 0x3f317217, v36
	s_nop 1
	v_add_f32_e32 v33, v33, v35
	v_mul_f32_e32 v35, 0x3e000000, v47
	v_mul_f32_e64 v36, |v35|, s37
	v_exp_f32_e32 v36, v36
	v_cmp_lt_i32_e32 vcc, v61, v102
	v_add_f32_e32 v36, 1.0, v36
	v_cndmask_b32_e64 v123, 0, -v33, vcc
	v_fma_f32 v33, v46, s81, -v33
	v_log_f32_e32 v36, v36
	s_nop 0
	v_cndmask_b32_e32 v46, v212, v33, vcc
	v_max_f32_e32 v33, 0, v35
	v_mul_f32_e32 v35, 0x3f317217, v36
	v_fma_f32 v35, v36, s83, -v35
	v_fmac_f32_e32 v35, 0x3377d1cf, v36
	v_fmac_f32_e32 v35, 0x3f317217, v36
	s_nop 1
	v_add_f32_e32 v33, v33, v35
	v_add_u32_e32 v35, 0x7b, v81
	v_cmp_lt_i32_e32 vcc, v35, v102
	s_nop 1
	v_cndmask_b32_e64 v35, 0, -v33, vcc
	v_fma_f32 v33, v47, s81, -v33
	v_cndmask_b32_e32 v36, v212, v33, vcc
	v_add_f32_e32 v33, v85, v103
	v_add_f32_e32 v47, v106, v108
	v_add_f32_e32 v61, v33, v47
	v_add_f32_e32 v47, v121, v122
	v_add_f32_e32 v85, v123, v35
	v_add_f32_e32 v47, v47, v85
	ds_bpermute_b32 v85, v110, v47
	v_add_f32_e32 v121, v41, v120
	v_add_f32_e32 v37, v37, v121
	ds_bpermute_b32 v121, v110, v37
	ds_bpermute_b32 v33, v110, v61
	s_waitcnt lgkmcnt(0)
	v_cndmask_b32_e64 v124, 0, v85, s[52:53]
	v_add_f32_e32 v124, v63, v124
	v_add_f32_e32 v36, v124, v36
	v_mul_f32_e32 v36, 0x3fb8aa3b, v36
	v_add_f32_e32 v35, v124, v35
	v_exp_f32_e32 v125, v36
	v_add_f32_e32 v36, v46, v35
	v_mul_f32_e32 v36, 0x3fb8aa3b, v36
	v_add_f32_e32 v35, v123, v35
	v_exp_f32_e32 v124, v36
	v_add_f32_e32 v36, v45, v35
	v_add_f32_e32 v35, v122, v35
	v_add_f32_e32 v35, v44, v35
	v_mul_f32_e32 v35, 0x3fb8aa3b, v35
	v_mul_f32_e32 v36, 0x3fb8aa3b, v36
	v_exp_f32_e32 v122, v35
	v_add_f32_e32 v35, v47, v85
	v_exp_f32_e32 v46, v36
	v_add_f32_e32 v35, v63, v35
	v_cndmask_b32_e64 v36, 0, v121, s[52:53]
	v_add_f32_e32 v36, v36, v35
	v_add_f32_e32 v43, v43, v36
	v_add_f32_e32 v36, v120, v36
	v_add_f32_e32 v42, v42, v36
	v_add_f32_e32 v36, v41, v36
	v_add_f32_e32 v40, v40, v36
	v_add_f32_e32 v36, v39, v36
	v_add_f32_e32 v36, v38, v36
	v_mul_f32_e32 v36, 0x3fb8aa3b, v36
	v_add_f32_e32 v63, v37, v121
	v_exp_f32_e32 v85, v36
	v_pk_add_f32 v[36:37], v[62:63], v[34:35]
	v_pk_add_f32 v[38:39], v[60:61], v[32:33]
	v_mul_f32_e32 v40, 0x3fb8aa3b, v40
	v_pk_add_f32 v[38:39], v[38:39], v[36:37]
	v_exp_f32_e32 v44, v40
	v_cndmask_b32_e64 v40, 0, v33, s[52:53]
	ds_bpermute_b32 v33, v110, v38
	v_add_f32_e32 v35, v40, v37
	v_add_f32_e32 v36, v109, v35
	v_add_f32_e32 v35, v108, v35
	v_mul_f32_e32 v42, 0x3fb8aa3b, v42
	s_waitcnt lgkmcnt(0)
	v_cndmask_b32_e64 v41, 0, v33, s[52:53]
	v_add_f32_e32 v41, v41, v39
	v_add_f32_e32 v37, v107, v35
	v_add_f32_e32 v35, v106, v35
	v_add_f32_e32 v34, v34, v41
	v_exp_f32_e32 v47, v42
	v_add_f32_e32 v40, v105, v35
	v_add_f32_e32 v35, v103, v35
	v_add_f32_e32 v42, v87, v41
	v_add_f32_e32 v41, v86, v34
	v_add_f32_e32 v34, v62, v34
	v_mul_f32_e32 v43, 0x3fb8aa3b, v43
	v_add_f32_e32 v35, v99, v35
	v_add_f32_e32 v32, v32, v34
	v_exp_f32_e32 v45, v43
	v_mul_f32_e32 v40, 0x3fb8aa3b, v40
	v_mul_f32_e32 v35, 0x3fb8aa3b, v35
	v_mul_f32_e32 v42, 0x3fb8aa3b, v42
	v_mul_f32_e32 v41, 0x3fb8aa3b, v41
	v_add_f32_e32 v43, v84, v34
	v_add_f32_e32 v32, v83, v32
	v_mul_f32_e32 v36, 0x3fb8aa3b, v36
	v_mul_f32_e32 v37, 0x3fb8aa3b, v37
	v_exp_f32_e32 v40, v40
	v_exp_f32_e32 v35, v35
	v_exp_f32_e32 v42, v42
	v_mul_f32_e32 v43, 0x3fb8aa3b, v43
	v_mul_f32_e32 v32, 0x3fb8aa3b, v32
	v_exp_f32_e32 v34, v41
	v_exp_f32_e32 v36, v36
	v_exp_f32_e32 v37, v37
	v_exp_f32_e32 v43, v43
	v_exp_f32_e32 v32, v32
	v_add_f32_e32 v33, v38, v33
	v_add_f32_e32 v63, v33, v39
	v_cvt_pk_bf16_f32 v33, v34, v42
	v_cvt_pk_bf16_f32 v34, v35, v40
	v_cvt_pk_bf16_f32 v32, v32, v43
	v_cvt_pk_bf16_f32 v35, v37, v36
	v_cvt_pk_bf16_f32 v44, v85, v44
	v_cvt_pk_bf16_f32 v45, v47, v45
	v_cvt_pk_bf16_f32 v46, v122, v46
	v_cvt_pk_bf16_f32 v47, v124, v125
	s_setprio 1
	s_waitcnt lgkmcnt(0)
	v_mfma_f32_32x32x16_bf16 v[16:31], v[180:183], v[32:35], v[16:31]
	v_mfma_f32_32x32x16_bf16 v[16:31], v[184:187], v[44:47], v[16:31]
	s_setprio 0
	s_setprio 1
	s_waitcnt lgkmcnt(0)
	v_mfma_f32_32x32x16_bf16 v[0:15], v[188:191], v[32:35], v[0:15]
	v_mfma_f32_32x32x16_bf16 v[0:15], v[192:195], v[44:47], v[0:15]
	s_setprio 0
	v_cmp_gt_f32_e32 vcc, s5, v63
	s_cmp_lg_u64 vcc, exec
	s_cselect_b64 s[14:15], -1, 0
.LBB0_793:
	s_add_i32 s16, s6, 64
	s_cmp_le_i32 s16, s18
	s_cselect_b64 s[16:17], -1, 0
	s_and_b64 s[16:17], s[16:17], s[14:15]
	s_andn2_b64 vcc, exec, s[16:17]
	s_cbranch_vccnz .LBB0_795
	ds_read_b128 v[32:35], v82
	ds_read_b128 v[84:87], v82 offset:32
	ds_read_b128 v[106:109], v82 offset:64
	ds_read_b128 v[120:123], v82 offset:96
	s_setprio 1
	s_waitcnt lgkmcnt(0)
	v_mfma_f32_32x32x16_bf16 v[32:47], v[32:35], v[64:67], 0
	v_mfma_f32_32x32x16_bf16 v[32:47], v[84:87], v[68:71], v[32:47]
	v_mfma_f32_32x32x16_bf16 v[32:47], v[106:109], v[72:75], v[32:47]
	v_mfma_f32_32x32x16_bf16 v[32:47], v[120:123], v[76:79], v[32:47]
	s_setprio 0
	s_nop 10
	v_add_u32_e32 v197, 0x2000, v80
	ds_read2_b64 v[180:183], v197 offset0:128 offset1:130
	ds_read2_b64 v[184:187], v197 offset0:132 offset1:134
	v_add_u32_e32 v197, 0x3000, v80
	ds_read2_b64 v[188:191], v197 offset0:160 offset1:162
	ds_read2_b64 v[192:195], v197 offset0:164 offset1:166
	v_mul_f32_e32 v60, 0x3e000000, v32
	v_mul_f32_e64 v61, |v60|, s37
	v_exp_f32_e32 v61, v61
	v_mul_f32_e32 v83, 0x3e000000, v33
	v_add_u32_e32 v62, 64, v81
	v_max_f32_e32 v60, 0, v60
	v_add_f32_e32 v61, 1.0, v61
	s_nop 1
	v_log_f32_e32 v61, v61
	s_nop 0
	v_mul_f32_e32 v84, 0x3f317217, v61
	v_fma_f32 v84, v61, s83, -v84
	v_fmac_f32_e32 v84, 0x3377d1cf, v61
	v_fmac_f32_e32 v84, 0x3f317217, v61
	s_nop 1
	v_mov_b32_e32 v61, v84
	v_mul_f32_e64 v82, |v83|, s37
	v_exp_f32_e32 v82, v82
	v_cmp_lt_i32_e32 vcc, v62, v102
	v_add_f32_e32 v61, v60, v61
	v_fma_f32 v32, v32, s81, -v61
	v_add_f32_e32 v62, 1.0, v82
	v_cndmask_b32_e64 v60, 0, -v61, vcc
	s_nop 0
	v_log_f32_e32 v62, v62
	s_nop 0
	v_cndmask_b32_e32 v82, v212, v32, vcc
	v_max_f32_e32 v32, 0, v83
	v_mul_f32_e32 v61, 0x3f317217, v62
	v_fma_f32 v61, v62, s83, -v61
	v_fmac_f32_e32 v61, 0x3377d1cf, v62
	v_fmac_f32_e32 v61, 0x3f317217, v62
	s_nop 1
	v_mul_f32_e32 v62, 0x3e000000, v34
	v_add_f32_e32 v61, v32, v61
	v_mul_f32_e64 v32, |v62|, s37
	v_exp_f32_e32 v83, v32
	v_add_u32_e32 v32, 0x41, v81
	v_cmp_lt_i32_e32 vcc, v32, v102
	v_fma_f32 v33, v33, s81, -v61
	v_add_f32_e32 v83, 1.0, v83
	v_cndmask_b32_e64 v32, 0, -v61, vcc
	s_nop 0
	v_log_f32_e32 v84, v83
	s_nop 0
	v_cndmask_b32_e32 v83, v212, v33, vcc
	v_max_f32_e32 v33, 0, v62
	v_mul_f32_e32 v61, 0x3f317217, v84
	v_fma_f32 v61, v84, s83, -v61
	v_fmac_f32_e32 v61, 0x3377d1cf, v84
	v_fmac_f32_e32 v61, 0x3f317217, v84
	s_nop 1
	v_add_f32_e32 v33, v33, v61
	v_mul_f32_e32 v61, 0x3e000000, v35
	v_mul_f32_e64 v62, |v61|, s37
	v_exp_f32_e32 v84, v62
	v_add_u32_e32 v62, 0x42, v81
	v_cmp_lt_i32_e32 vcc, v62, v102
	v_add_f32_e32 v84, 1.0, v84
	v_cndmask_b32_e64 v62, 0, -v33, vcc
	v_fma_f32 v33, v34, s81, -v33
	v_log_f32_e32 v84, v84
	s_nop 0
	v_cndmask_b32_e32 v85, v212, v33, vcc
	v_max_f32_e32 v33, 0, v61
	v_mul_f32_e32 v34, 0x3f317217, v84
	v_fma_f32 v34, v84, s83, -v34
	v_fmac_f32_e32 v34, 0x3377d1cf, v84
	v_fmac_f32_e32 v34, 0x3f317217, v84
	s_nop 1
	v_mul_f32_e32 v61, 0x3e000000, v36
	v_add_f32_e32 v33, v33, v34
	v_mul_f32_e64 v34, |v61|, s37
	v_exp_f32_e32 v84, v34
	v_add_u32_e32 v34, 0x43, v81
	v_cmp_lt_i32_e32 vcc, v34, v102
	v_add_f32_e32 v84, 1.0, v84
	v_cndmask_b32_e64 v34, 0, -v33, vcc
	v_fma_f32 v33, v35, s81, -v33
	v_log_f32_e32 v84, v84
	s_nop 0
	v_cndmask_b32_e32 v86, v212, v33, vcc
	v_max_f32_e32 v33, 0, v61
	v_mul_f32_e32 v35, 0x3f317217, v84
	v_fma_f32 v35, v84, s83, -v35
	v_fmac_f32_e32 v35, 0x3377d1cf, v84
	v_fmac_f32_e32 v35, 0x3f317217, v84
	s_nop 1
	v_add_f32_e32 v33, v33, v35
	v_mul_f32_e32 v35, 0x3e000000, v37
	v_mul_f32_e64 v61, |v35|, s37
	v_exp_f32_e32 v61, v61
	v_add_u32_e32 v84, 0x48, v81
	v_cmp_lt_i32_e32 vcc, v84, v102
	v_add_f32_e32 v61, 1.0, v61
	v_cndmask_b32_e64 v84, 0, -v33, vcc
	v_fma_f32 v33, v36, s81, -v33
	v_log_f32_e32 v61, v61
	s_nop 0
	v_cndmask_b32_e32 v87, v212, v33, vcc
	v_max_f32_e32 v33, 0, v35
	v_mul_f32_e32 v35, 0x3f317217, v61
	v_fma_f32 v35, v61, s83, -v35
	v_fmac_f32_e32 v35, 0x3377d1cf, v61
	v_fmac_f32_e32 v35, 0x3f317217, v61
	s_nop 1
	v_add_f32_e32 v33, v33, v35
	v_mul_f32_e32 v35, 0x3e000000, v38
	v_mul_f32_e64 v36, |v35|, s37
	v_exp_f32_e32 v36, v36
	v_add_u32_e32 v61, 0x49, v81
	v_cmp_lt_i32_e32 vcc, v61, v102
	v_add_f32_e32 v36, 1.0, v36
	v_cndmask_b32_e64 v99, 0, -v33, vcc
	v_fma_f32 v33, v37, s81, -v33
	v_log_f32_e32 v36, v36
	s_nop 0
	v_cndmask_b32_e32 v103, v212, v33, vcc
	v_max_f32_e32 v33, 0, v35
	v_add_u32_e32 v37, 0x4a, v81
	v_mul_f32_e32 v35, 0x3f317217, v36
	v_fma_f32 v35, v36, s83, -v35
	v_fmac_f32_e32 v35, 0x3377d1cf, v36
	v_fmac_f32_e32 v35, 0x3f317217, v36
	s_nop 1
	v_add_f32_e32 v33, v33, v35
	v_mul_f32_e32 v35, 0x3e000000, v39
	v_mul_f32_e64 v36, |v35|, s37
	v_exp_f32_e32 v36, v36
	v_cmp_lt_i32_e32 vcc, v37, v102
	v_add_f32_e32 v36, 1.0, v36
	v_cndmask_b32_e64 v105, 0, -v33, vcc
	v_fma_f32 v33, v38, s81, -v33
	v_log_f32_e32 v36, v36
	s_nop 0
	v_cndmask_b32_e32 v106, v212, v33, vcc
	v_max_f32_e32 v33, 0, v35
	v_add_u32_e32 v37, 0x4b, v81
	v_mul_f32_e32 v35, 0x3f317217, v36
	v_fma_f32 v35, v36, s83, -v35
	v_fmac_f32_e32 v35, 0x3377d1cf, v36
	v_fmac_f32_e32 v35, 0x3f317217, v36
	s_nop 1
	v_add_f32_e32 v33, v33, v35
	v_mul_f32_e32 v35, 0x3e000000, v40
	v_mul_f32_e64 v36, |v35|, s37
	v_exp_f32_e32 v36, v36
	v_cmp_lt_i32_e32 vcc, v37, v102
	v_add_f32_e32 v36, 1.0, v36
	v_cndmask_b32_e64 v107, 0, -v33, vcc
	v_fma_f32 v33, v39, s81, -v33
	v_log_f32_e32 v36, v36
	s_nop 0
	v_cndmask_b32_e32 v108, v212, v33, vcc
	v_max_f32_e32 v33, 0, v35
	v_add_u32_e32 v37, 0x50, v81
	v_mul_f32_e32 v35, 0x3f317217, v36
	v_fma_f32 v35, v36, s83, -v35
	v_fmac_f32_e32 v35, 0x3377d1cf, v36
	v_fmac_f32_e32 v35, 0x3f317217, v36
	v_add_u32_e32 v39, 0x51, v81
	s_nop 0
	v_add_f32_e32 v33, v33, v35
	v_mul_f32_e32 v35, 0x3e000000, v41
	v_mul_f32_e64 v36, |v35|, s37
	v_exp_f32_e32 v36, v36
	v_cmp_lt_i32_e32 vcc, v37, v102
	v_add_f32_e32 v36, 1.0, v36
	v_cndmask_b32_e64 v37, 0, -v33, vcc
	v_fma_f32 v33, v40, s81, -v33
	v_log_f32_e32 v36, v36
	s_nop 0
	v_cndmask_b32_e32 v38, v212, v33, vcc
	v_max_f32_e32 v33, 0, v35
	v_mul_f32_e32 v35, 0x3f317217, v36
	v_fma_f32 v35, v36, s83, -v35
	v_fmac_f32_e32 v35, 0x3377d1cf, v36
	v_fmac_f32_e32 v35, 0x3f317217, v36
	s_nop 1
	v_add_f32_e32 v33, v33, v35
	v_mul_f32_e32 v35, 0x3e000000, v42
	v_mul_f32_e64 v36, |v35|, s37
	v_exp_f32_e32 v36, v36
	v_cmp_lt_i32_e32 vcc, v39, v102
	v_add_f32_e32 v36, 1.0, v36
	v_cndmask_b32_e64 v39, 0, -v33, vcc
	v_fma_f32 v33, v41, s81, -v33
	v_log_f32_e32 v36, v36
	s_nop 0
	v_cndmask_b32_e32 v40, v212, v33, vcc
	v_max_f32_e32 v33, 0, v35
	v_add_u32_e32 v41, 0x52, v81
	v_mul_f32_e32 v35, 0x3f317217, v36
	v_fma_f32 v35, v36, s83, -v35
	v_fmac_f32_e32 v35, 0x3377d1cf, v36
	v_fmac_f32_e32 v35, 0x3f317217, v36
	v_add_f32_e32 v37, v37, v39
	s_nop 0
	v_add_f32_e32 v33, v33, v35
	v_mul_f32_e32 v35, 0x3e000000, v43
	v_mul_f32_e64 v36, |v35|, s37
	v_exp_f32_e32 v36, v36
	v_cmp_lt_i32_e32 vcc, v41, v102
	v_add_f32_e32 v36, 1.0, v36
	v_cndmask_b32_e64 v41, 0, -v33, vcc
	v_fma_f32 v33, v42, s81, -v33
	v_log_f32_e32 v36, v36
	s_nop 0
	v_cndmask_b32_e32 v42, v212, v33, vcc
	v_max_f32_e32 v33, 0, v35
	v_add_u32_e32 v61, 0x53, v81
	v_mul_f32_e32 v35, 0x3f317217, v36
	v_fma_f32 v35, v36, s83, -v35
	v_fmac_f32_e32 v35, 0x3377d1cf, v36
	v_fmac_f32_e32 v35, 0x3f317217, v36
	s_nop 1
	v_add_f32_e32 v33, v33, v35
	v_mul_f32_e32 v35, 0x3e000000, v44
	v_mul_f32_e64 v36, |v35|, s37
	v_exp_f32_e32 v36, v36
	v_cmp_lt_i32_e32 vcc, v61, v102
	v_add_f32_e32 v36, 1.0, v36
	v_cndmask_b32_e64 v109, 0, -v33, vcc
	v_fma_f32 v33, v43, s81, -v33
	v_log_f32_e32 v36, v36
	s_nop 0
	v_cndmask_b32_e32 v43, v212, v33, vcc
	v_max_f32_e32 v33, 0, v35
	v_add_u32_e32 v61, 0x58, v81
	v_mul_f32_e32 v35, 0x3f317217, v36
	v_fma_f32 v35, v36, s83, -v35
	v_fmac_f32_e32 v35, 0x3377d1cf, v36
	v_fmac_f32_e32 v35, 0x3f317217, v36
	s_nop 1
	v_add_f32_e32 v33, v33, v35
	v_mul_f32_e32 v35, 0x3e000000, v45
	v_mul_f32_e64 v36, |v35|, s37
	v_exp_f32_e32 v36, v36
	v_cmp_lt_i32_e32 vcc, v61, v102
	v_add_f32_e32 v36, 1.0, v36
	v_cndmask_b32_e64 v120, 0, -v33, vcc
	v_fma_f32 v33, v44, s81, -v33
	v_log_f32_e32 v36, v36
	s_nop 0
	v_cndmask_b32_e32 v44, v212, v33, vcc
	v_max_f32_e32 v33, 0, v35
	v_add_u32_e32 v61, 0x59, v81
	v_mul_f32_e32 v35, 0x3f317217, v36
	v_fma_f32 v35, v36, s83, -v35
	v_fmac_f32_e32 v35, 0x3377d1cf, v36
	v_fmac_f32_e32 v35, 0x3f317217, v36
	s_nop 1
	v_add_f32_e32 v33, v33, v35
	v_mul_f32_e32 v35, 0x3e000000, v46
	v_mul_f32_e64 v36, |v35|, s37
	v_exp_f32_e32 v36, v36
	v_cmp_lt_i32_e32 vcc, v61, v102
	v_add_f32_e32 v36, 1.0, v36
	v_cndmask_b32_e64 v121, 0, -v33, vcc
	v_fma_f32 v33, v45, s81, -v33
	v_log_f32_e32 v36, v36
	s_nop 0
	v_cndmask_b32_e32 v45, v212, v33, vcc
	v_max_f32_e32 v33, 0, v35
	v_add_u32_e32 v61, 0x5a, v81
	v_mul_f32_e32 v35, 0x3f317217, v36
	v_fma_f32 v35, v36, s83, -v35
	v_fmac_f32_e32 v35, 0x3377d1cf, v36
	v_fmac_f32_e32 v35, 0x3f317217, v36
	s_nop 1
	v_add_f32_e32 v33, v33, v35
	v_mul_f32_e32 v35, 0x3e000000, v47
	v_mul_f32_e64 v36, |v35|, s37
	v_exp_f32_e32 v36, v36
	v_cmp_lt_i32_e32 vcc, v61, v102
	v_add_f32_e32 v36, 1.0, v36
	v_cndmask_b32_e64 v122, 0, -v33, vcc
	v_fma_f32 v33, v46, s81, -v33
	v_log_f32_e32 v36, v36
	s_nop 0
	v_cndmask_b32_e32 v46, v212, v33, vcc
	v_max_f32_e32 v33, 0, v35
	v_mul_f32_e32 v35, 0x3f317217, v36
	v_fma_f32 v35, v36, s83, -v35
	v_fmac_f32_e32 v35, 0x3377d1cf, v36
	v_fmac_f32_e32 v35, 0x3f317217, v36
	s_nop 1
	v_add_f32_e32 v33, v33, v35
	v_add_u32_e32 v35, 0x5b, v81
	v_cmp_lt_i32_e32 vcc, v35, v102
	s_nop 1
	v_cndmask_b32_e64 v35, 0, -v33, vcc
	v_fma_f32 v33, v47, s81, -v33
	v_cndmask_b32_e32 v36, v212, v33, vcc
	v_add_f32_e32 v33, v84, v99
	v_add_f32_e32 v47, v105, v107
	v_add_f32_e32 v61, v33, v47
	v_add_f32_e32 v47, v120, v121
	v_add_f32_e32 v81, v122, v35
	v_add_f32_e32 v47, v47, v81
	ds_bpermute_b32 v81, v110, v47
	v_add_f32_e32 v84, v41, v109
	v_add_f32_e32 v37, v37, v84
	ds_bpermute_b32 v84, v110, v37
	ds_bpermute_b32 v33, v110, v61
	s_waitcnt lgkmcnt(0)
	v_cndmask_b32_e64 v120, 0, v81, s[52:53]
	v_add_f32_e32 v120, v63, v120
	v_add_f32_e32 v36, v120, v36
	v_mul_f32_e32 v36, 0x3fb8aa3b, v36
	v_add_f32_e32 v35, v120, v35
	v_exp_f32_e32 v123, v36
	v_add_f32_e32 v36, v46, v35
	v_mul_f32_e32 v36, 0x3fb8aa3b, v36
	v_add_f32_e32 v35, v122, v35
	v_exp_f32_e32 v120, v36
	v_add_f32_e32 v36, v45, v35
	v_add_f32_e32 v35, v121, v35
	v_add_f32_e32 v35, v44, v35
	v_mul_f32_e32 v35, 0x3fb8aa3b, v35
	v_mul_f32_e32 v36, 0x3fb8aa3b, v36
	v_exp_f32_e32 v121, v35
	v_add_f32_e32 v35, v47, v81
	v_exp_f32_e32 v46, v36
	v_add_f32_e32 v35, v63, v35
	v_cndmask_b32_e64 v36, 0, v84, s[52:53]
	v_add_f32_e32 v36, v36, v35
	v_add_f32_e32 v43, v43, v36
	v_add_f32_e32 v36, v109, v36
	v_add_f32_e32 v42, v42, v36
	v_add_f32_e32 v36, v41, v36
	v_add_f32_e32 v40, v40, v36
	v_add_f32_e32 v36, v39, v36
	v_add_f32_e32 v36, v38, v36
	v_mul_f32_e32 v36, 0x3fb8aa3b, v36
	v_add_f32_e32 v63, v37, v84
	v_exp_f32_e32 v81, v36
	v_pk_add_f32 v[36:37], v[62:63], v[34:35]
	v_pk_add_f32 v[38:39], v[60:61], v[32:33]
	v_mul_f32_e32 v40, 0x3fb8aa3b, v40
	v_pk_add_f32 v[38:39], v[38:39], v[36:37]
	v_exp_f32_e32 v44, v40
	v_cndmask_b32_e64 v40, 0, v33, s[52:53]
	ds_bpermute_b32 v33, v110, v38
	v_add_f32_e32 v35, v40, v37
	v_add_f32_e32 v36, v108, v35
	v_add_f32_e32 v35, v107, v35
	v_mul_f32_e32 v42, 0x3fb8aa3b, v42
	s_waitcnt lgkmcnt(0)
	v_cndmask_b32_e64 v41, 0, v33, s[52:53]
	v_add_f32_e32 v41, v41, v39
	v_add_f32_e32 v37, v106, v35
	v_add_f32_e32 v35, v105, v35
	v_add_f32_e32 v34, v34, v41
	v_exp_f32_e32 v47, v42
	v_add_f32_e32 v40, v103, v35
	v_add_f32_e32 v35, v99, v35
	v_add_f32_e32 v42, v86, v41
	v_add_f32_e32 v41, v85, v34
	v_add_f32_e32 v34, v62, v34
	v_mul_f32_e32 v43, 0x3fb8aa3b, v43
	v_add_f32_e32 v35, v87, v35
	v_add_f32_e32 v32, v32, v34
	v_exp_f32_e32 v45, v43
	v_mul_f32_e32 v40, 0x3fb8aa3b, v40
	v_mul_f32_e32 v35, 0x3fb8aa3b, v35
	v_mul_f32_e32 v42, 0x3fb8aa3b, v42
	v_mul_f32_e32 v41, 0x3fb8aa3b, v41
	v_add_f32_e32 v43, v83, v34
	v_add_f32_e32 v32, v82, v32
	v_mul_f32_e32 v36, 0x3fb8aa3b, v36
	v_mul_f32_e32 v37, 0x3fb8aa3b, v37
	v_exp_f32_e32 v40, v40
	v_exp_f32_e32 v35, v35
	v_exp_f32_e32 v42, v42
	v_mul_f32_e32 v43, 0x3fb8aa3b, v43
	v_mul_f32_e32 v32, 0x3fb8aa3b, v32
	v_exp_f32_e32 v34, v41
	v_exp_f32_e32 v36, v36
	v_exp_f32_e32 v37, v37
	v_exp_f32_e32 v43, v43
	v_exp_f32_e32 v32, v32
	v_add_f32_e32 v33, v38, v33
	v_add_f32_e32 v63, v33, v39
	v_cvt_pk_bf16_f32 v33, v34, v42
	v_cvt_pk_bf16_f32 v34, v35, v40
	v_cvt_pk_bf16_f32 v32, v32, v43
	v_cvt_pk_bf16_f32 v35, v37, v36
	v_cvt_pk_bf16_f32 v44, v81, v44
	v_cvt_pk_bf16_f32 v45, v47, v45
	v_cvt_pk_bf16_f32 v46, v121, v46
	v_cvt_pk_bf16_f32 v47, v120, v123
	s_setprio 1
	s_waitcnt lgkmcnt(0)
	v_mfma_f32_32x32x16_bf16 v[16:31], v[180:183], v[32:35], v[16:31]
	v_mfma_f32_32x32x16_bf16 v[16:31], v[184:187], v[44:47], v[16:31]
	s_setprio 0
	s_setprio 1
	s_waitcnt lgkmcnt(0)
	v_mfma_f32_32x32x16_bf16 v[0:15], v[188:191], v[32:35], v[0:15]
	v_mfma_f32_32x32x16_bf16 v[0:15], v[192:195], v[44:47], v[0:15]
	s_setprio 0
	v_cmp_gt_f32_e32 vcc, s5, v63
	s_cmp_lg_u64 vcc, exec
	s_cselect_b64 s[14:15], -1, 0
